# prompt attention loop: one static s_setprio 1 for waves 4-7, reset after the loop
# baseline (speedup 1.0000x reference)
; __device__ __forceinline__ void attn_main_unit(const Ctx& C, int b, int h, int j, unsigned char* shm) {
;     const int tid = opaque_tid(), lane = tid & 63, qi = lane & 31, hi = lane >> 5, w = __builtin_amdgcn_readfirstlane(tid >> 6);
;     const int tq0 = 16 + 256 * j + 32 * w, tq = tq0 + qi;
;     const size_t qrow = (size_t)b * TP + tq;
;     bf16x8 qf[4];
; #pragma unroll
;     for (int s = 0; s < 4; ++s) qf[s] = *(const bf16x8*)(C.Q + qrow * 512 + 64 * h + 16 * s + 8 * hi);
;     f32x16 o0, o1;
; #pragma unroll
;     for (int r = 0; r < 16; ++r) { o0[r] = 0.f; o1[r] = 0.f; }
;     float carry = 1.f;
;     const int itop = 4 * j + 4, wtop = 4 * j + (32 * w + 94) / 64;
;     const int srow = tid >> 3, sch = tid & 7;
;     const bf16_t* kg = C.KP + ((ptrdiff_t)b * TP - 48 + srow) * 512 + 64 * h + 8 * sch;
;     const bf16_t* vg = C.VB + ((ptrdiff_t)b * TP - 48 + srow) * 512 + 64 * h + 8 * sch;
;     u32x4 kreg = *(const u32x4*)(kg + (size_t)itop * 64 * 512), vreg = *(const u32x4*)(vg + (size_t)itop * 64 * 512);
;     unsigned* flg = (unsigned*)(shm + 2 * AT_BUF);
;     if (tid < 2) flg[tid] = 0u;
;     bool wdone = false;
;     for (int i = itop; i >= 0; --i) {
;         unsigned char* kb_ = shm + (i & 1) * AT_BUF; unsigned char* vb_ = kb_ + AT_KBYTES;
;         *(u32x4*)(kb_ + srow * AT_KROW + sch * 16) = kreg;
;         {
;             bf16_t* vw = (bf16_t*)(vb_ + (8 * sch) * AT_VROW + srow * 2);
;             vw[0 * (AT_VROW / 2)] = (bf16_t)(vreg.x & 0xffffu); vw[1 * (AT_VROW / 2)] = (bf16_t)(vreg.x >> 16);
;             vw[2 * (AT_VROW / 2)] = (bf16_t)(vreg.y & 0xffffu); vw[3 * (AT_VROW / 2)] = (bf16_t)(vreg.y >> 16);
;             vw[4 * (AT_VROW / 2)] = (bf16_t)(vreg.z & 0xffffu); vw[5 * (AT_VROW / 2)] = (bf16_t)(vreg.z >> 16);
;             vw[6 * (AT_VROW / 2)] = (bf16_t)(vreg.w & 0xffffu); vw[7 * (AT_VROW / 2)] = (bf16_t)(vreg.w >> 16);
;         }
;         if (i > 0) { kreg = *(const u32x4*)(kg + (size_t)(i - 1) * 64 * 512); vreg = *(const u32x4*)(vg + (size_t)(i - 1) * 64 * 512); }
; __device__ __forceinline__ void mixers_phase(const Ctx& C, int l, unsigned char* shm, int sub) {
;     ...
;     if (sub & 1) for (int u = blockIdx.x; u < 256; u += G) {
;         const int bh = (u & 7) * 4 + (u >> 6), jp = (u >> 3) & 7;
;     ...
;         attn_main_unit(C, bh >> 3, bh & 7, 15 - jp, shm);
;         attn_main_unit(C, bh >> 3, bh & 7, jp, shm);
;     ...
;     }
.LBB0_503:
	s_and_b64 vcc, exec, s[0:1]
	s_cbranch_vccz .LBB0_826
	v_readlane_b32 s0, v252, 1
	v_readlane_b32 s1, v252, 2
	s_waitcnt lgkmcnt(0)
	s_load_dword s47, s[0:1], 0x0
	v_readlane_b32 s0, v252, 59
	v_readlane_b32 s1, v252, 60
	s_andn2_b64 vcc, exec, s[0:1]
	v_readlane_b32 s14, v252, 0
	s_movk_i32 s28, 0x90
	s_movk_i32 s29, 0xffef
	s_movk_i32 s34, 0xffee
	s_movk_i32 s35, 0xffed
	s_movk_i32 s36, 0xffec
	s_movk_i32 s37, 0xffe7
	s_movk_i32 s44, 0xffe6
	s_movk_i32 s45, 0xffe5
	s_movk_i32 s46, 0xffe4
	v_readfirstlane_b32 s2, v195
	s_lshr_b32 s2, s2, 6
	s_cmp_ge_u32 s2, 4
	s_cbranch_scc0 .Lattn_prio_done
	s_setprio 1
.Lattn_prio_done:
	s_cbranch_vccz .LBB0_508
.LBB0_505:
	s_setprio 0
	v_readlane_b32 s0, v252, 61
	v_readlane_b32 s1, v252, 62
	s_andn2_b64 vcc, exec, s[0:1]
	s_cbranch_vccnz .LBB0_619
	v_readlane_b32 s0, v254, 51
	v_readlane_b32 s1, v254, 52
	s_mov_b32 s2, s0
	s_ashr_i32 s3, s0, 31
	s_lshl_b64 s[0:1], s[2:3], 24
	v_writelane_b32 v251, s0, 5
	v_readlane_b32 s25, v252, 0
	s_nop 0
	v_writelane_b32 v251, s1, 6
	s_mov_b32 s0, s2
	v_writelane_b32 v254, s0, 51
	s_nop 1
	v_writelane_b32 v254, s1, 52
	s_lshl_b64 s[0:1], s[2:3], 18
	v_writelane_b32 v251, s0, 7
	s_nop 1
	v_writelane_b32 v251, s1, 8
	s_waitcnt lgkmcnt(0)
	v_writelane_b32 v251, s47, 9
	s_branch .LBB0_604
